# ctx norm: partial-sum loads batched 4 at a time
# speedup vs baseline: 1.0110x; 1.0022x over previous
; __device__ __forceinline__ void norm_phase(const float* xlat, const float* xctx, float* XC, const float* P, int npart, bf16* H, float* SS, const float* g, const float* modl, int jshift, int row_begin, int Mrows) {
;     ...
;         if (row >= MLAT) {
;             const float* pr = P + (size_t)(row - MLAT) * DM;
;             for (int sp = 0; sp < npart; ++sp) {
; #pragma unroll
;                 for (int j = 0; j < 4; ++j) v[j] += *((const f32x4*)(pr + (size_t)sp * MCTX * DM) + lane + 64 * j); }
.LBB0_168:
	s_cmp_lt_u32 s12, 4
	s_cbranch_scc1 .Lnp_single
	s_mov_b64 s[14:15], 0x400000
	global_load_dwordx4 v[36:39], v[28:29], off
	global_load_dwordx4 v[40:43], v[28:29], off offset:1024
	global_load_dwordx4 v[44:47], v[28:29], off offset:2048
	global_load_dwordx4 v[48:51], v[28:29], off offset:3072
	v_lshl_add_u64 v[28:29], v[28:29], 0, s[14:15]
	global_load_dwordx4 v[52:55], v[28:29], off
	global_load_dwordx4 v[56:59], v[28:29], off offset:1024
	global_load_dwordx4 v[60:63], v[28:29], off offset:2048
	global_load_dwordx4 v[64:67], v[28:29], off offset:3072
	v_lshl_add_u64 v[28:29], v[28:29], 0, s[14:15]
	global_load_dwordx4 v[100:103], v[28:29], off
	global_load_dwordx4 v[104:107], v[28:29], off offset:1024
	global_load_dwordx4 v[108:111], v[28:29], off offset:2048
	global_load_dwordx4 v[112:115], v[28:29], off offset:3072
	v_lshl_add_u64 v[28:29], v[28:29], 0, s[14:15]
	global_load_dwordx4 v[116:119], v[28:29], off
	global_load_dwordx4 v[120:123], v[28:29], off offset:1024
	global_load_dwordx4 v[124:127], v[28:29], off offset:2048
	global_load_dwordx4 v[128:131], v[28:29], off offset:3072
	v_lshl_add_u64 v[28:29], v[28:29], 0, s[14:15]
	s_add_i32 s12, s12, -4
	s_waitcnt vmcnt(12)
	v_pk_add_f32 v[14:15], v[14:15], v[38:39]
	v_pk_add_f32 v[12:13], v[12:13], v[36:37]
	v_pk_add_f32 v[10:11], v[10:11], v[42:43]
	v_pk_add_f32 v[8:9], v[8:9], v[40:41]
	v_pk_add_f32 v[6:7], v[6:7], v[46:47]
	v_pk_add_f32 v[4:5], v[4:5], v[44:45]
	v_pk_add_f32 v[2:3], v[2:3], v[50:51]
	v_pk_add_f32 v[0:1], v[0:1], v[48:49]
	s_waitcnt vmcnt(8)
	v_pk_add_f32 v[14:15], v[14:15], v[54:55]
	v_pk_add_f32 v[12:13], v[12:13], v[52:53]
	v_pk_add_f32 v[10:11], v[10:11], v[58:59]
	v_pk_add_f32 v[8:9], v[8:9], v[56:57]
	v_pk_add_f32 v[6:7], v[6:7], v[62:63]
	v_pk_add_f32 v[4:5], v[4:5], v[60:61]
	v_pk_add_f32 v[2:3], v[2:3], v[66:67]
	v_pk_add_f32 v[0:1], v[0:1], v[64:65]
	s_waitcnt vmcnt(4)
	v_pk_add_f32 v[14:15], v[14:15], v[102:103]
	v_pk_add_f32 v[12:13], v[12:13], v[100:101]
	v_pk_add_f32 v[10:11], v[10:11], v[106:107]
	v_pk_add_f32 v[8:9], v[8:9], v[104:105]
	v_pk_add_f32 v[6:7], v[6:7], v[110:111]
	v_pk_add_f32 v[4:5], v[4:5], v[108:109]
	v_pk_add_f32 v[2:3], v[2:3], v[114:115]
	v_pk_add_f32 v[0:1], v[0:1], v[112:113]
	s_waitcnt vmcnt(0)
	v_pk_add_f32 v[14:15], v[14:15], v[118:119]
	v_pk_add_f32 v[12:13], v[12:13], v[116:117]
	v_pk_add_f32 v[10:11], v[10:11], v[122:123]
	v_pk_add_f32 v[8:9], v[8:9], v[120:121]
	v_pk_add_f32 v[6:7], v[6:7], v[126:127]
	v_pk_add_f32 v[4:5], v[4:5], v[124:125]
	v_pk_add_f32 v[2:3], v[2:3], v[130:131]
	v_pk_add_f32 v[0:1], v[0:1], v[128:129]
	s_cmp_eq_u32 s12, 0
	s_cbranch_scc0 .LBB0_168
	s_branch .Lnp_done

; __device__ __forceinline__ void norm_phase(const float* xlat, const float* xctx, float* XC, const float* P, int npart, bf16* H, float* SS, const float* g, const float* modl, int jshift, int row_begin, int Mrows) {
;     ...
;             for (int j = 0; j < 4; ++j) *((f32x4*)(XC + (size_t)(row - MLAT) * DM) + lane + 64 * j) = v[j];
.Lnp_done:
	s_lshl_b64 s[12:13], s[24:25], 12
	v_lshl_add_u64 v[28:29], v[18:19], 0, s[12:13]
	global_store_dwordx4 v[28:29], v[12:15], off
	global_store_dwordx4 v[28:29], v[8:11], off offset:1024
	global_store_dwordx4 v[28:29], v[4:7], off offset:2048
	global_store_dwordx4 v[28:29], v[0:3], off offset:3072
